# attention unit epilogue: read-back of the exchanged map-1 values software-pipelined (8 LDS reads in flight into dead staging registers, counted lgkmcnt waits)
# baseline (speedup 1.0000x reference)
; __device__ __forceinline__ void attn_unit(const bf16* __restrict__ P, bf16* __restrict__ MIXIN, const float* __restrict__ gn, int seq0, int h, int q0, int nt, float kmax0, float kmax1, float slope, float lam, char* lds) {
;     ...
;   if (mpe == 0) {
;     float g4[4];
; #pragma unroll
;     for (int d0 = 0; d0 < 4; ++d0) g4[d0] = gn[d0 * 32 + r32e] * 0.8f;
; #pragma unroll
;     for (int d0 = 0; d0 < 4; ++d0)
; #pragma unroll
;       for (int r = 0; r < 16; ++r) o[d0][r] = o[d0][r] * rli[r] - X[(wqe * 64 + d0 * 16 + r) * 64 + lanee];
;     bf16* Ow = MIXIN + (size_t)(seq0 + q0 + wqe * 32) * DM + h * 128 + r32e;
; #pragma unroll
;     for (int r = 0; r < 16; ++r) {
;       float ss = o[0][r] * o[0][r] + o[1][r] * o[1][r] + o[2][r] * o[2][r] + o[3][r] * o[3][r];
;       ss += __shfl_xor(ss, 1); ss += __shfl_xor(ss, 2); ss += __shfl_xor(ss, 4); ss += __shfl_xor(ss, 8); ss += __shfl_xor(ss, 16);
.LBB0_344:
	s_or_b64 exec, exec, s[0:1]
	v_cmp_gt_u32_e32 vcc, s28, v77
	s_waitcnt lgkmcnt(0)
	s_barrier
	s_and_saveexec_b64 s[6:7], vcc
	s_cbranch_execz .LBB0_291
	v_lshl_add_u32 v97, v68, 2, 0
	v_add_u32_e32 v98, v97, v69
	ds_read2st64_b32 v[154:155], v98 offset1:1
	ds_read2st64_b32 v[156:157], v98 offset0:2 offset1:3
	ds_read2st64_b32 v[158:159], v98 offset0:4 offset1:5
	ds_read2st64_b32 v[160:161], v98 offset0:6 offset1:7
	ds_read2st64_b32 v[162:163], v98 offset0:8 offset1:9
	ds_read2st64_b32 v[164:165], v98 offset0:10 offset1:11
	ds_read2st64_b32 v[166:167], v98 offset0:14 offset1:15
	ds_read2st64_b32 v[168:169], v98 offset0:12 offset1:13
	v_lshlrev_b32_e32 v67, 2, v76
	global_load_dword v64, v67, s[8:9]
	global_load_dword v65, v67, s[8:9] offset:128
	global_load_dword v66, v67, s[8:9] offset:256
	s_waitcnt lgkmcnt(7)
	v_fma_f32 v75, v48, v94, -v154
	v_fma_f32 v74, v49, v96, -v155
	ds_read2st64_b32 v[170:171], v98 offset0:16 offset1:17
	global_load_dword v67, v67, s[8:9] offset:384
	s_add_i32 s0, s35, s31
	s_lshl_b32 s10, s24, 1
	s_waitcnt lgkmcnt(7)
	v_fma_f32 v73, v50, v92, -v156
	v_fma_f32 v72, v51, v93, -v157
	ds_read2st64_b32 v[172:173], v98 offset0:18 offset1:19
	s_waitcnt lgkmcnt(7)
	v_fma_f32 v71, v52, v89, -v158
	v_fma_f32 v70, v53, v91, -v159
	ds_read2st64_b32 v[186:187], v98 offset0:20 offset1:21
	s_waitcnt lgkmcnt(7)
	v_fma_f32 v69, v54, v80, -v160
	v_fma_f32 v68, v55, v81, -v161
	ds_read2st64_b32 v[188:189], v98 offset0:22 offset1:23
	s_waitcnt lgkmcnt(7)
	v_fma_f32 v55, v56, v87, -v162
	v_fma_f32 v54, v57, v88, -v163
	ds_read2st64_b32 v[190:191], v98 offset0:24 offset1:25
	ds_read2st64_b32 v[192:193], v98 offset0:26 offset1:27
	s_waitcnt lgkmcnt(8)
	v_fma_f32 v53, v58, v85, -v164
	v_fma_f32 v52, v59, v86, -v165
	ds_read2st64_b32 v[194:195], v98 offset0:30 offset1:31
	s_waitcnt lgkmcnt(7)
	v_fma_f32 v51, v60, v83, -v168
	v_fma_f32 v50, v61, v84, -v169
	v_fma_f32 v49, v62, v82, -v166
	v_fma_f32 v48, v63, v79, -v167
	ds_read2st64_b32 v[196:197], v98 offset0:28 offset1:29
	s_waitcnt lgkmcnt(7)
	v_fma_f32 v63, v32, v94, -v170
	v_fma_f32 v62, v33, v96, -v171
	ds_read2st64_b32 v[198:199], v98 offset0:32 offset1:33
	s_waitcnt lgkmcnt(7)
	v_fma_f32 v61, v34, v92, -v172
	v_fma_f32 v60, v35, v93, -v173
	ds_read2st64_b32 v[200:201], v98 offset0:34 offset1:35
	s_waitcnt lgkmcnt(7)
	v_fma_f32 v59, v36, v89, -v186
	v_fma_f32 v58, v37, v91, -v187
	ds_read2st64_b32 v[202:203], v98 offset0:36 offset1:37
	s_waitcnt lgkmcnt(7)
	v_fma_f32 v57, v38, v80, -v188
	v_fma_f32 v56, v39, v81, -v189
	ds_read2st64_b32 v[204:205], v98 offset0:38 offset1:39
	s_waitcnt vmcnt(3)
	v_mul_f32_e32 v64, 0x3f4ccccd, v64
	s_waitcnt vmcnt(2)
	v_mul_f32_e32 v65, 0x3f4ccccd, v65
	s_waitcnt lgkmcnt(7)
	v_fma_f32 v39, v40, v87, -v190
	v_fma_f32 v38, v41, v88, -v191
	ds_read2st64_b32 v[206:207], v98 offset0:40 offset1:41
	ds_read2st64_b32 v[208:209], v98 offset0:42 offset1:43
	s_waitcnt vmcnt(1)
	v_mul_f32_e32 v66, 0x3f4ccccd, v66
	s_waitcnt vmcnt(0)
	v_mul_f32_e32 v67, 0x3f4ccccd, v67
	s_waitcnt lgkmcnt(8)
	v_fma_f32 v37, v42, v85, -v192
	v_fma_f32 v36, v43, v86, -v193
	ds_read2st64_b32 v[154:155], v98 offset0:44 offset1:45
	s_waitcnt lgkmcnt(7)
	v_fma_f32 v35, v44, v83, -v196
	v_fma_f32 v34, v45, v84, -v197
	v_fma_f32 v33, v46, v82, -v194
	v_fma_f32 v32, v47, v79, -v195
	ds_read2st64_b32 v[156:157], v98 offset0:46 offset1:47
	s_waitcnt lgkmcnt(7)
	v_fma_f32 v95, v16, v94, -v198
	v_fma_f32 v46, v17, v96, -v199
	ds_read2st64_b32 v[158:159], v98 offset0:48 offset1:49
	s_waitcnt lgkmcnt(7)
	v_fma_f32 v45, v18, v92, -v200
	v_fma_f32 v44, v19, v93, -v201
	ds_read2st64_b32 v[160:161], v98 offset0:50 offset1:51
	s_waitcnt lgkmcnt(7)
	v_fma_f32 v43, v20, v89, -v202
	v_fma_f32 v42, v21, v91, -v203
	s_waitcnt lgkmcnt(6)
	v_fma_f32 v41, v22, v80, -v204
	v_fma_f32 v40, v23, v81, -v205
	s_waitcnt lgkmcnt(5)
	v_fma_f32 v24, v24, v87, -v206
	v_fma_f32 v23, v25, v88, -v207
	s_waitcnt lgkmcnt(4)
	v_fma_f32 v21, v26, v85, -v208
	v_fma_f32 v20, v27, v86, -v209
	s_waitcnt lgkmcnt(3)
	v_fma_f32 v19, v28, v83, -v154
	v_fma_f32 v18, v29, v84, -v155
	s_waitcnt lgkmcnt(2)
	v_fma_f32 v17, v30, v82, -v156
	v_fma_f32 v16, v31, v79, -v157
	s_waitcnt lgkmcnt(1)
	v_fma_f32 v99, v0, v94, -v158
	v_fma_f32 v94, v1, v96, -v159
	s_waitcnt lgkmcnt(0)
	v_fma_f32 v47, v2, v92, -v160
	v_mul_f32_e32 v2, v63, v63
	v_fmac_f32_e32 v2, v75, v75
	v_fmac_f32_e32 v2, v95, v95
	v_fmac_f32_e32 v2, v99, v99
	v_fma_f32 v31, v3, v93, -v161
	ds_read2st64_b32 v[0:1], v98 offset0:52 offset1:53
	ds_bpermute_b32 v3, v228, v2
	s_waitcnt lgkmcnt(1)
	v_fma_f32 v30, v4, v89, -v0
	v_fma_f32 v29, v5, v91, -v1
	ds_read2st64_b32 v[0:1], v98 offset0:54 offset1:55
	s_waitcnt lgkmcnt(1)
	v_add_f32_e32 v2, v2, v3
	ds_bpermute_b32 v3, v227, v2
	s_waitcnt lgkmcnt(1)
	v_fma_f32 v28, v6, v80, -v0
	v_fma_f32 v27, v7, v81, -v1
	ds_read2st64_b32 v[0:1], v98 offset0:56 offset1:57
	s_waitcnt lgkmcnt(1)
	v_add_f32_e32 v2, v2, v3
	ds_bpermute_b32 v3, v226, v2
	s_waitcnt lgkmcnt(1)
	v_fma_f32 v26, v8, v87, -v0
	v_fma_f32 v25, v9, v88, -v1
	ds_read2st64_b32 v[0:1], v98 offset0:58 offset1:59
	s_waitcnt lgkmcnt(1)
	v_add_f32_e32 v2, v2, v3
	ds_bpermute_b32 v3, v225, v2
	s_waitcnt lgkmcnt(1)
	v_fma_f32 v22, v10, v85, -v0
	v_fma_f32 v10, v11, v86, -v1
	ds_read2st64_b32 v[0:1], v98 offset0:60 offset1:61
	s_waitcnt lgkmcnt(1)
	v_add_f32_e32 v2, v2, v3
	ds_bpermute_b32 v3, v224, v2
	s_waitcnt lgkmcnt(1)
	v_fma_f32 v9, v12, v83, -v0
	ds_read_b32 v0, v98 offset:15872
	s_waitcnt lgkmcnt(1)
	v_add_f32_e32 v2, v2, v3
	v_fmamk_f32 v2, v2, 0x3c000000, v221
	v_cmp_gt_f32_e32 vcc, s26, v2
	v_mul_f32_e32 v3, 0x4f800000, v2
	s_waitcnt lgkmcnt(0)
; __device__ __forceinline__ unsigned f2bf(float f) { unsigned u = __builtin_bit_cast(unsigned, f); return (u + 0x7fffu + ((u >> 16) & 1u)) >> 16; }
; __device__ __forceinline__ int crow(int r, int hi) { return (r & 3) + 8 * (r >> 2) + 4 * hi; }
; __device__ __forceinline__ void attn_unit(const bf16* __restrict__ P, bf16* __restrict__ MIXIN, const float* __restrict__ gn, int seq0, int h, int q0, int nt, float kmax0, float kmax1, float slope, float lam, char* lds) {
;     ...
;     for (int r = 0; r < 16; ++r) {
;       float ss = o[0][r] * o[0][r] + o[1][r] * o[1][r] + o[2][r] * o[2][r] + o[3][r] * o[3][r];
;       ss += __shfl_xor(ss, 1); ss += __shfl_xor(ss, 2); ss += __shfl_xor(ss, 4); ss += __shfl_xor(ss, 8); ss += __shfl_xor(ss, 16);
;       const float sc_ = 1.0f / sqrtf(ss * (1.0f / 128.0f) + EPS);
;       const int orow = crow(r, hie);
; #pragma unroll
;       for (int d0 = 0; d0 < 4; ++d0) Ow[(size_t)orow * DM + d0 * 32] = (bf16)f2bf(o[d0][r] * sc_ * g4[d0]);
;     }
	v_fma_f32 v7, v14, v82, -v0
	v_or_b32_e32 v0, 0x3f00, v90
	v_add_u32_e32 v0, v97, v0
	ds_read_b32 v0, v0
	v_cndmask_b32_e32 v2, v2, v3, vcc
	v_sqrt_f32_e32 v3, v2
	v_fma_f32 v8, v13, v84, -v1
	s_waitcnt lgkmcnt(0)
	v_fma_f32 v6, v15, v79, -v0
	v_lshlrev_b32_e32 v0, 10, v77
	v_add_u32_e32 v4, -1, v3
	v_and_b32_e32 v0, 0x30000, v0
	v_fma_f32 v5, -v4, v3, v2
	v_lshl_or_b32 v176, s0, 11, v0
	v_cmp_ge_f32_e64 s[0:1], 0, v5
	v_add_u32_e32 v5, 1, v3
	v_lshl_add_u64 v[0:1], s[46:47], 0, v[176:177]
	v_cndmask_b32_e64 v4, v3, v4, s[0:1]
	v_fma_f32 v3, -v5, v3, v2
	v_cmp_lt_f32_e64 s[0:1], 0, v3
	v_lshl_add_u64 v[0:1], v[0:1], 0, s[10:11]
	v_lshlrev_b32_e32 v176, 1, v76
	v_cndmask_b32_e64 v3, v4, v5, s[0:1]
	v_mul_f32_e32 v4, 0x37800000, v3
	v_cndmask_b32_e32 v3, v3, v4, vcc
	v_cmp_class_f32_e32 vcc, v2, v220
	v_lshl_add_u64 v[0:1], v[0:1], 0, v[176:177]
	v_lshlrev_b32_e32 v176, 13, v78
	v_cndmask_b32_e32 v2, v3, v2, vcc
	v_div_scale_f32 v3, s[0:1], v2, v2, 1.0
	v_rcp_f32_e32 v4, v3
	v_lshl_add_u64 v[0:1], v[0:1], 0, v[176:177]
	v_fma_f32 v5, -v3, v4, 1.0
	v_fmac_f32_e32 v4, v5, v4
	v_div_scale_f32 v5, vcc, 1.0, v2, 1.0
	v_mul_f32_e32 v11, v5, v4
	v_fma_f32 v12, -v3, v11, v5
	v_fmac_f32_e32 v11, v12, v4
	v_fma_f32 v3, -v3, v11, v5
	v_div_fmas_f32 v3, v3, v4, v11
	v_div_fixup_f32 v2, v3, v2, 1.0
	v_mul_f32_e32 v3, v75, v2
	v_mul_f32_e32 v3, v64, v3
	v_bfe_u32 v4, v3, 16, 1
	v_add3_u32 v3, v3, v4, s30
	global_store_short_d16_hi v[0:1], v3, off
	v_mul_f32_e32 v3, v63, v2
	v_mul_f32_e32 v3, v65, v3
	v_bfe_u32 v4, v3, 16, 1
	v_add3_u32 v3, v3, v4, s30
	global_store_short_d16_hi v[0:1], v3, off offset:64
	v_mul_f32_e32 v3, v95, v2
	v_mul_f32_e32 v3, v66, v3
	v_bfe_u32 v4, v3, 16, 1
	v_mul_f32_e32 v2, v99, v2
	v_add3_u32 v3, v3, v4, s30
	v_mul_f32_e32 v2, v67, v2
	global_store_short_d16_hi v[0:1], v3, off offset:128
	v_bfe_u32 v3, v2, 16, 1
	v_add3_u32 v2, v2, v3, s30
	global_store_short_d16_hi v[0:1], v2, off offset:192
	v_mul_f32_e32 v2, v62, v62
	v_fmac_f32_e32 v2, v74, v74
	v_fmac_f32_e32 v2, v46, v46
	v_fmac_f32_e32 v2, v94, v94
	s_nop 1
	s_waitcnt lgkmcnt(0)
	v_add_f32_dpp v2, v2, v2 quad_perm:[1,0,3,2] row_mask:0xf bank_mask:0xf
	s_nop 1
	s_waitcnt lgkmcnt(0)
	v_add_f32_dpp v2, v2, v2 quad_perm:[2,3,0,1] row_mask:0xf bank_mask:0xf
	s_nop 1
	s_waitcnt lgkmcnt(0)
	v_add_f32_dpp v2, v2, v2 row_half_mirror row_mask:0xf bank_mask:0xf
	s_nop 1
	s_waitcnt lgkmcnt(0)
	v_add_f32_dpp v2, v2, v2 row_mirror row_mask:0xf bank_mask:0xf
	v_mov_b32_e32 v3, v2
	s_waitcnt lgkmcnt(0)
	s_nop 0
	v_permlane16_swap_b32_e32 v2, v3
	v_add_f32_e32 v2, v2, v3
	v_fmamk_f32 v2, v2, 0x3c000000, v221
	v_cmp_gt_f32_e32 vcc, s26, v2
	v_mul_f32_e32 v3, 0x4f800000, v2
	s_nop 0
	v_cndmask_b32_e32 v2, v2, v3, vcc
	v_sqrt_f32_e32 v3, v2
	s_nop 0
	v_add_u32_e32 v4, -1, v3
	v_fma_f32 v5, -v4, v3, v2
	v_cmp_ge_f32_e64 s[0:1], 0, v5
	v_add_u32_e32 v5, 1, v3
	s_nop 0
	v_cndmask_b32_e64 v4, v3, v4, s[0:1]
	v_fma_f32 v3, -v5, v3, v2
	v_cmp_lt_f32_e64 s[0:1], 0, v3
	s_nop 1
	v_cndmask_b32_e64 v3, v4, v5, s[0:1]
	v_mul_f32_e32 v4, 0x37800000, v3
	v_cndmask_b32_e32 v3, v3, v4, vcc
	v_cmp_class_f32_e32 vcc, v2, v220
	s_nop 1
	v_cndmask_b32_e32 v2, v3, v2, vcc
	v_div_scale_f32 v3, s[0:1], v2, v2, 1.0
	v_rcp_f32_e32 v4, v3
	s_nop 0
	v_fma_f32 v5, -v3, v4, 1.0
	v_fmac_f32_e32 v4, v5, v4
	v_div_scale_f32 v5, vcc, 1.0, v2, 1.0
	v_mul_f32_e32 v11, v5, v4
	v_fma_f32 v12, -v3, v11, v5
	v_fmac_f32_e32 v11, v12, v4
	v_fma_f32 v3, -v3, v11, v5
	v_div_fmas_f32 v3, v3, v4, v11
	v_div_fixup_f32 v2, v3, v2, 1.0
	v_mul_f32_e32 v3, v74, v2
	v_mul_f32_e32 v3, v64, v3
	v_bfe_u32 v4, v3, 16, 1
	v_add3_u32 v3, v3, v4, s30
	global_store_short_d16_hi v[0:1], v3, off offset:2048
	v_mul_f32_e32 v3, v62, v2
	v_mul_f32_e32 v3, v65, v3
	v_bfe_u32 v4, v3, 16, 1
	v_add3_u32 v3, v3, v4, s30
	global_store_short_d16_hi v[0:1], v3, off offset:2112
	v_mul_f32_e32 v3, v46, v2
	v_mul_f32_e32 v3, v66, v3
	v_bfe_u32 v4, v3, 16, 1
	v_mul_f32_e32 v2, v94, v2
	v_add3_u32 v3, v3, v4, s30
	v_mul_f32_e32 v2, v67, v2
	global_store_short_d16_hi v[0:1], v3, off offset:2176
	v_bfe_u32 v3, v2, 16, 1
	v_add3_u32 v2, v2, v3, s30
	global_store_short_d16_hi v[0:1], v2, off offset:2240
	v_mul_f32_e32 v2, v61, v61
	v_fmac_f32_e32 v2, v73, v73
	v_fmac_f32_e32 v2, v45, v45
	v_fmac_f32_e32 v2, v47, v47
	s_nop 1
	s_waitcnt lgkmcnt(0)
	v_add_f32_dpp v2, v2, v2 quad_perm:[1,0,3,2] row_mask:0xf bank_mask:0xf
	s_nop 1
	s_waitcnt lgkmcnt(0)
	v_add_f32_dpp v2, v2, v2 quad_perm:[2,3,0,1] row_mask:0xf bank_mask:0xf
	s_nop 1
	s_waitcnt lgkmcnt(0)
	v_add_f32_dpp v2, v2, v2 row_half_mirror row_mask:0xf bank_mask:0xf
	s_nop 1
	s_waitcnt lgkmcnt(0)
	v_add_f32_dpp v2, v2, v2 row_mirror row_mask:0xf bank_mask:0xf
	v_mov_b32_e32 v3, v2
	s_waitcnt lgkmcnt(0)
; __device__ __forceinline__ unsigned f2bf(float f) { unsigned u = __builtin_bit_cast(unsigned, f); return (u + 0x7fffu + ((u >> 16) & 1u)) >> 16; }
; __device__ __forceinline__ int crow(int r, int hi) { return (r & 3) + 8 * (r >> 2) + 4 * hi; }
; __device__ __forceinline__ void attn_unit(const bf16* __restrict__ P, bf16* __restrict__ MIXIN, const float* __restrict__ gn, int seq0, int h, int q0, int nt, float kmax0, float kmax1, float slope, float lam, char* lds) {
;     ...
;     for (int r = 0; r < 16; ++r) {
;       float ss = o[0][r] * o[0][r] + o[1][r] * o[1][r] + o[2][r] * o[2][r] + o[3][r] * o[3][r];
;       ss += __shfl_xor(ss, 1); ss += __shfl_xor(ss, 2); ss += __shfl_xor(ss, 4); ss += __shfl_xor(ss, 8); ss += __shfl_xor(ss, 16);
;       const float sc_ = 1.0f / sqrtf(ss * (1.0f / 128.0f) + EPS);
;       const int orow = crow(r, hie);
; #pragma unroll
;       for (int d0 = 0; d0 < 4; ++d0) Ow[(size_t)orow * DM + d0 * 32] = (bf16)f2bf(o[d0][r] * sc_ * g4[d0]);
;     }
	s_nop 0
	v_permlane16_swap_b32_e32 v2, v3
	v_add_f32_e32 v2, v2, v3
	v_fmamk_f32 v2, v2, 0x3c000000, v221
	v_cmp_gt_f32_e32 vcc, s26, v2
	v_mul_f32_e32 v3, 0x4f800000, v2
	s_nop 0
	v_cndmask_b32_e32 v2, v2, v3, vcc
	v_sqrt_f32_e32 v3, v2
	s_nop 0
	v_add_u32_e32 v4, -1, v3
	v_fma_f32 v5, -v4, v3, v2
	v_cmp_ge_f32_e64 s[0:1], 0, v5
	v_add_u32_e32 v5, 1, v3
	s_nop 0
	v_cndmask_b32_e64 v4, v3, v4, s[0:1]
	v_fma_f32 v3, -v5, v3, v2
	v_cmp_lt_f32_e64 s[0:1], 0, v3
	s_nop 1
	v_cndmask_b32_e64 v3, v4, v5, s[0:1]
	v_mul_f32_e32 v4, 0x37800000, v3
	v_cndmask_b32_e32 v3, v3, v4, vcc
	v_cmp_class_f32_e32 vcc, v2, v220
	s_nop 1
	v_cndmask_b32_e32 v2, v3, v2, vcc
	v_div_scale_f32 v3, s[0:1], v2, v2, 1.0
	v_rcp_f32_e32 v4, v3
	s_movk_i32 s0, 0x1000
	v_fma_f32 v5, -v3, v4, 1.0
	v_fmac_f32_e32 v4, v5, v4
	v_div_scale_f32 v5, vcc, 1.0, v2, 1.0
	v_mul_f32_e32 v11, v5, v4
	v_fma_f32 v12, -v3, v11, v5
	v_fmac_f32_e32 v11, v12, v4
	v_fma_f32 v3, -v3, v11, v5
	v_div_fmas_f32 v3, v3, v4, v11
	v_div_fixup_f32 v4, v3, v2, 1.0
	v_mul_f32_e32 v2, v73, v4
	v_mul_f32_e32 v2, v64, v2
	v_bfe_u32 v3, v2, 16, 1
	v_add3_u32 v5, v2, v3, s30
	v_add_co_u32_e32 v2, vcc, s0, v0
	s_nop 1
	v_addc_co_u32_e32 v3, vcc, 0, v1, vcc
	global_store_short_d16_hi v[2:3], v5, off
	v_mul_f32_e32 v5, v61, v4
	v_mul_f32_e32 v5, v65, v5
	v_bfe_u32 v11, v5, 16, 1
	v_add3_u32 v5, v5, v11, s30
	global_store_short_d16_hi v[2:3], v5, off offset:64
	v_mul_f32_e32 v5, v45, v4
	v_mul_f32_e32 v5, v66, v5
	v_bfe_u32 v11, v5, 16, 1
	v_mul_f32_e32 v4, v47, v4
	v_add3_u32 v5, v5, v11, s30
	v_mul_f32_e32 v4, v67, v4
	global_store_short_d16_hi v[2:3], v5, off offset:128
	v_bfe_u32 v5, v4, 16, 1
	v_add3_u32 v4, v4, v5, s30
	global_store_short_d16_hi v[2:3], v4, off offset:192
	v_mul_f32_e32 v4, v60, v60
	v_fmac_f32_e32 v4, v72, v72
	v_fmac_f32_e32 v4, v44, v44
	v_fmac_f32_e32 v4, v31, v31
	s_nop 1
	s_waitcnt lgkmcnt(0)
	v_add_f32_dpp v4, v4, v4 quad_perm:[1,0,3,2] row_mask:0xf bank_mask:0xf
	s_nop 1
	s_waitcnt lgkmcnt(0)
	v_add_f32_dpp v4, v4, v4 quad_perm:[2,3,0,1] row_mask:0xf bank_mask:0xf
	s_nop 1
	s_waitcnt lgkmcnt(0)
	v_add_f32_dpp v4, v4, v4 row_half_mirror row_mask:0xf bank_mask:0xf
	s_nop 1
	s_waitcnt lgkmcnt(0)
	v_add_f32_dpp v4, v4, v4 row_mirror row_mask:0xf bank_mask:0xf
	v_mov_b32_e32 v5, v4
	s_waitcnt lgkmcnt(0)
	s_nop 0
	v_permlane16_swap_b32_e32 v4, v5
	v_add_f32_e32 v4, v4, v5
	v_fmamk_f32 v4, v4, 0x3c000000, v221
	v_cmp_gt_f32_e32 vcc, s26, v4
	v_mul_f32_e32 v5, 0x4f800000, v4
	s_nop 0
	v_cndmask_b32_e32 v4, v4, v5, vcc
	v_sqrt_f32_e32 v5, v4
	s_nop 0
	v_add_u32_e32 v11, -1, v5
	v_fma_f32 v12, -v11, v5, v4
	v_cmp_ge_f32_e64 s[0:1], 0, v12
	v_add_u32_e32 v12, 1, v5
	s_nop 0
	v_cndmask_b32_e64 v11, v5, v11, s[0:1]
	v_fma_f32 v5, -v12, v5, v4
	v_cmp_lt_f32_e64 s[0:1], 0, v5
	s_nop 1
	v_cndmask_b32_e64 v5, v11, v12, s[0:1]
	v_mul_f32_e32 v11, 0x37800000, v5
	v_cndmask_b32_e32 v5, v5, v11, vcc
	v_cmp_class_f32_e32 vcc, v4, v220
	s_nop 1
	v_cndmask_b32_e32 v4, v5, v4, vcc
	v_div_scale_f32 v5, s[0:1], v4, v4, 1.0
	v_rcp_f32_e32 v11, v5
	s_nop 0
	v_fma_f32 v12, -v5, v11, 1.0
	v_fmac_f32_e32 v11, v12, v11
	v_div_scale_f32 v12, vcc, 1.0, v4, 1.0
	v_mul_f32_e32 v13, v12, v11
	v_fma_f32 v14, -v5, v13, v12
	v_fmac_f32_e32 v13, v14, v11
	v_fma_f32 v5, -v5, v13, v12
	v_div_fmas_f32 v5, v5, v11, v13
	v_div_fixup_f32 v4, v5, v4, 1.0
	v_mul_f32_e32 v5, v72, v4
	v_mul_f32_e32 v5, v64, v5
	v_bfe_u32 v11, v5, 16, 1
	v_add3_u32 v5, v5, v11, s30
	global_store_short_d16_hi v[2:3], v5, off offset:2048
	v_mul_f32_e32 v5, v60, v4
	v_mul_f32_e32 v5, v65, v5
	v_bfe_u32 v11, v5, 16, 1
	v_add3_u32 v5, v5, v11, s30
	global_store_short_d16_hi v[2:3], v5, off offset:2112
	v_mul_f32_e32 v5, v44, v4
	v_mul_f32_e32 v5, v66, v5
	v_bfe_u32 v11, v5, 16, 1
	v_mul_f32_e32 v4, v31, v4
	v_add3_u32 v5, v5, v11, s30
	v_mul_f32_e32 v4, v67, v4
	global_store_short_d16_hi v[2:3], v5, off offset:2176
	v_bfe_u32 v5, v4, 16, 1
	v_add3_u32 v4, v4, v5, s30
	global_store_short_d16_hi v[2:3], v4, off offset:2240
	v_mul_f32_e32 v2, v59, v59
	v_fmac_f32_e32 v2, v71, v71
	v_fmac_f32_e32 v2, v43, v43
	v_fmac_f32_e32 v2, v30, v30
	s_nop 1
	s_waitcnt lgkmcnt(0)
	v_add_f32_dpp v2, v2, v2 quad_perm:[1,0,3,2] row_mask:0xf bank_mask:0xf
	s_nop 1
	s_waitcnt lgkmcnt(0)
	v_add_f32_dpp v2, v2, v2 quad_perm:[2,3,0,1] row_mask:0xf bank_mask:0xf
	s_nop 1
	s_waitcnt lgkmcnt(0)
	v_add_f32_dpp v2, v2, v2 row_half_mirror row_mask:0xf bank_mask:0xf
	s_nop 1
	s_waitcnt lgkmcnt(0)
	v_add_f32_dpp v2, v2, v2 row_mirror row_mask:0xf bank_mask:0xf
	v_mov_b32_e32 v3, v2
	s_waitcnt lgkmcnt(0)
	s_nop 0
	v_permlane16_swap_b32_e32 v2, v3
	v_add_f32_e32 v2, v2, v3
	v_fmamk_f32 v2, v2, 0x3c000000, v221
	v_cmp_gt_f32_e32 vcc, s26, v2
	v_mul_f32_e32 v3, 0x4f800000, v2
	s_nop 0
	v_cndmask_b32_e32 v2, v2, v3, vcc
	v_sqrt_f32_e32 v3, v2
	s_nop 0
	v_add_u32_e32 v4, -1, v3
	v_fma_f32 v5, -v4, v3, v2
	v_cmp_ge_f32_e64 s[0:1], 0, v5
	v_add_u32_e32 v5, 1, v3
	s_nop 0
	v_cndmask_b32_e64 v4, v3, v4, s[0:1]
	v_fma_f32 v3, -v5, v3, v2
	v_cmp_lt_f32_e64 s[0:1], 0, v3
	s_nop 1
	v_cndmask_b32_e64 v3, v4, v5, s[0:1]
	v_mul_f32_e32 v4, 0x37800000, v3
	v_cndmask_b32_e32 v3, v3, v4, vcc
	v_cmp_class_f32_e32 vcc, v2, v220
	s_nop 1
	v_cndmask_b32_e32 v2, v3, v2, vcc
	v_div_scale_f32 v3, s[0:1], v2, v2, 1.0
	v_rcp_f32_e32 v4, v3
	s_movk_i32 s0, 0x4000
	v_fma_f32 v5, -v3, v4, 1.0
	v_fmac_f32_e32 v4, v5, v4
	v_div_scale_f32 v5, vcc, 1.0, v2, 1.0
	v_mul_f32_e32 v11, v5, v4
	v_fma_f32 v12, -v3, v11, v5
	v_fmac_f32_e32 v11, v12, v4
	v_fma_f32 v3, -v3, v11, v5
	v_div_fmas_f32 v3, v3, v4, v11
	v_div_fixup_f32 v11, v3, v2, 1.0
	v_mul_f32_e32 v2, v71, v11
	v_mul_f32_e32 v2, v64, v2
	v_add_co_u32_e32 v4, vcc, s0, v0
	v_bfe_u32 v3, v2, 16, 1
	s_nop 0
	v_addc_co_u32_e32 v5, vcc, 0, v1, vcc
	s_movk_i32 s0, 0x5000
	v_add3_u32 v12, v2, v3, s30
	v_add_co_u32_e32 v2, vcc, s0, v0
	s_nop 1
	v_addc_co_u32_e32 v3, vcc, 0, v1, vcc
	global_store_short_d16_hi v[2:3], v12, off offset:-4096
	v_mul_f32_e32 v12, v59, v11
	v_mul_f32_e32 v12, v65, v12
	v_bfe_u32 v13, v12, 16, 1
	v_add3_u32 v12, v12, v13, s30
	global_store_short_d16_hi v[4:5], v12, off offset:64
	v_mul_f32_e32 v12, v43, v11
	v_mul_f32_e32 v12, v66, v12
	v_bfe_u32 v13, v12, 16, 1
	v_mul_f32_e32 v11, v30, v11
	v_add3_u32 v12, v12, v13, s30
	v_mul_f32_e32 v11, v67, v11
	global_store_short_d16_hi v[4:5], v12, off offset:128
	v_bfe_u32 v12, v11, 16, 1
	v_add3_u32 v11, v11, v12, s30
	global_store_short_d16_hi v[4:5], v11, off offset:192
	v_mul_f32_e32 v11, v58, v58
	v_fmac_f32_e32 v11, v70, v70
	v_fmac_f32_e32 v11, v42, v42
	v_fmac_f32_e32 v11, v29, v29
	s_nop 1
	s_waitcnt lgkmcnt(0)
; __device__ __forceinline__ unsigned f2bf(float f) { unsigned u = __builtin_bit_cast(unsigned, f); return (u + 0x7fffu + ((u >> 16) & 1u)) >> 16; }
; __device__ __forceinline__ int crow(int r, int hi) { return (r & 3) + 8 * (r >> 2) + 4 * hi; }
; __device__ __forceinline__ void attn_unit(const bf16* __restrict__ P, bf16* __restrict__ MIXIN, const float* __restrict__ gn, int seq0, int h, int q0, int nt, float kmax0, float kmax1, float slope, float lam, char* lds) {
;     ...
;     for (int r = 0; r < 16; ++r) {
;       float ss = o[0][r] * o[0][r] + o[1][r] * o[1][r] + o[2][r] * o[2][r] + o[3][r] * o[3][r];
;       ss += __shfl_xor(ss, 1); ss += __shfl_xor(ss, 2); ss += __shfl_xor(ss, 4); ss += __shfl_xor(ss, 8); ss += __shfl_xor(ss, 16);
;       const float sc_ = 1.0f / sqrtf(ss * (1.0f / 128.0f) + EPS);
;       const int orow = crow(r, hie);
; #pragma unroll
;       for (int d0 = 0; d0 < 4; ++d0) Ow[(size_t)orow * DM + d0 * 32] = (bf16)f2bf(o[d0][r] * sc_ * g4[d0]);
;     }
	v_add_f32_dpp v11, v11, v11 quad_perm:[1,0,3,2] row_mask:0xf bank_mask:0xf
	s_nop 1
	s_waitcnt lgkmcnt(0)
	v_add_f32_dpp v11, v11, v11 quad_perm:[2,3,0,1] row_mask:0xf bank_mask:0xf
	s_nop 1
	s_waitcnt lgkmcnt(0)
	v_add_f32_dpp v11, v11, v11 row_half_mirror row_mask:0xf bank_mask:0xf
	s_nop 1
	s_waitcnt lgkmcnt(0)
	v_add_f32_dpp v11, v11, v11 row_mirror row_mask:0xf bank_mask:0xf
	v_mov_b32_e32 v12, v11
	s_waitcnt lgkmcnt(0)
	s_nop 0
	v_permlane16_swap_b32_e32 v11, v12
	v_add_f32_e32 v11, v11, v12
	v_fmamk_f32 v11, v11, 0x3c000000, v221
	v_cmp_gt_f32_e32 vcc, s26, v11
	v_mul_f32_e32 v12, 0x4f800000, v11
	s_nop 0
	v_cndmask_b32_e32 v11, v11, v12, vcc
	v_sqrt_f32_e32 v12, v11
	s_nop 0
	v_add_u32_e32 v13, -1, v12
	v_fma_f32 v14, -v13, v12, v11
	v_cmp_ge_f32_e64 s[0:1], 0, v14
	v_add_u32_e32 v14, 1, v12
	s_nop 0
	v_cndmask_b32_e64 v13, v12, v13, s[0:1]
	v_fma_f32 v12, -v14, v12, v11
	v_cmp_lt_f32_e64 s[0:1], 0, v12
	s_nop 1
	v_cndmask_b32_e64 v12, v13, v14, s[0:1]
	v_mul_f32_e32 v13, 0x37800000, v12
	v_cndmask_b32_e32 v12, v12, v13, vcc
	v_cmp_class_f32_e32 vcc, v11, v220
	s_nop 1
	v_cndmask_b32_e32 v11, v12, v11, vcc
	v_div_scale_f32 v12, s[0:1], v11, v11, 1.0
	v_rcp_f32_e32 v13, v12
	s_nop 0
	v_fma_f32 v14, -v12, v13, 1.0
	v_fmac_f32_e32 v13, v14, v13
	v_div_scale_f32 v14, vcc, 1.0, v11, 1.0
	v_mul_f32_e32 v15, v14, v13
	v_fma_f32 v30, -v12, v15, v14
	v_fmac_f32_e32 v15, v30, v13
	v_fma_f32 v12, -v12, v15, v14
	v_div_fmas_f32 v12, v12, v13, v15
	v_div_fixup_f32 v11, v12, v11, 1.0
	v_mul_f32_e32 v12, v70, v11
	v_mul_f32_e32 v12, v64, v12
	v_bfe_u32 v13, v12, 16, 1
	v_add3_u32 v12, v12, v13, s30
	global_store_short_d16_hi v[4:5], v12, off offset:2048
	v_mul_f32_e32 v12, v58, v11
	v_mul_f32_e32 v12, v65, v12
	v_bfe_u32 v13, v12, 16, 1
	v_add3_u32 v12, v12, v13, s30
	global_store_short_d16_hi v[4:5], v12, off offset:2112
	v_mul_f32_e32 v12, v42, v11
	v_mul_f32_e32 v12, v66, v12
	v_bfe_u32 v13, v12, 16, 1
	v_mul_f32_e32 v11, v29, v11
	v_add3_u32 v12, v12, v13, s30
	v_mul_f32_e32 v11, v67, v11
	global_store_short_d16_hi v[4:5], v12, off offset:2176
	v_bfe_u32 v12, v11, 16, 1
	v_add3_u32 v11, v11, v12, s30
	global_store_short_d16_hi v[4:5], v11, off offset:2240
	v_mul_f32_e32 v4, v57, v57
	v_fmac_f32_e32 v4, v69, v69
	v_fmac_f32_e32 v4, v41, v41
	v_fmac_f32_e32 v4, v28, v28
	s_nop 1
	s_waitcnt lgkmcnt(0)
	v_add_f32_dpp v4, v4, v4 quad_perm:[1,0,3,2] row_mask:0xf bank_mask:0xf
	s_nop 1
	s_waitcnt lgkmcnt(0)
	v_add_f32_dpp v4, v4, v4 quad_perm:[2,3,0,1] row_mask:0xf bank_mask:0xf
	s_nop 1
	s_waitcnt lgkmcnt(0)
	v_add_f32_dpp v4, v4, v4 row_half_mirror row_mask:0xf bank_mask:0xf
	s_nop 1
	s_waitcnt lgkmcnt(0)
	v_add_f32_dpp v4, v4, v4 row_mirror row_mask:0xf bank_mask:0xf
	v_mov_b32_e32 v5, v4
	s_waitcnt lgkmcnt(0)
	s_nop 0
	v_permlane16_swap_b32_e32 v4, v5
	v_add_f32_e32 v4, v4, v5
	v_fmamk_f32 v4, v4, 0x3c000000, v221
	v_cmp_gt_f32_e32 vcc, s26, v4
	v_mul_f32_e32 v5, 0x4f800000, v4
	s_nop 0
	v_cndmask_b32_e32 v4, v4, v5, vcc
	v_sqrt_f32_e32 v5, v4
	s_nop 0
	v_add_u32_e32 v11, -1, v5
	v_fma_f32 v12, -v11, v5, v4
	v_cmp_ge_f32_e64 s[0:1], 0, v12
	v_add_u32_e32 v12, 1, v5
	s_nop 0
	v_cndmask_b32_e64 v11, v5, v11, s[0:1]
	v_fma_f32 v5, -v12, v5, v4
	v_cmp_lt_f32_e64 s[0:1], 0, v5
	s_nop 1
	v_cndmask_b32_e64 v5, v11, v12, s[0:1]
	v_mul_f32_e32 v11, 0x37800000, v5
	v_cndmask_b32_e32 v5, v5, v11, vcc
	v_cmp_class_f32_e32 vcc, v4, v220
	s_nop 1
	v_cndmask_b32_e32 v4, v5, v4, vcc
	v_div_scale_f32 v5, s[0:1], v4, v4, 1.0
	v_rcp_f32_e32 v11, v5
	s_nop 0
	v_fma_f32 v12, -v5, v11, 1.0
	v_fmac_f32_e32 v11, v12, v11
	v_div_scale_f32 v12, vcc, 1.0, v4, 1.0
	v_mul_f32_e32 v13, v12, v11
	v_fma_f32 v14, -v5, v13, v12
	v_fmac_f32_e32 v13, v14, v11
	v_fma_f32 v5, -v5, v13, v12
	v_div_fmas_f32 v5, v5, v11, v13
	v_div_fixup_f32 v4, v5, v4, 1.0
	v_mul_f32_e32 v5, v69, v4
	v_mul_f32_e32 v5, v64, v5
	v_bfe_u32 v11, v5, 16, 1
	v_add3_u32 v5, v5, v11, s30
	global_store_short_d16_hi v[2:3], v5, off
	v_mul_f32_e32 v5, v57, v4
	v_mul_f32_e32 v5, v65, v5
	v_bfe_u32 v11, v5, 16, 1
	v_add3_u32 v5, v5, v11, s30
	global_store_short_d16_hi v[2:3], v5, off offset:64
	v_mul_f32_e32 v5, v41, v4
	v_mul_f32_e32 v5, v66, v5
	v_bfe_u32 v11, v5, 16, 1
	v_mul_f32_e32 v4, v28, v4
	v_add3_u32 v5, v5, v11, s30
	v_mul_f32_e32 v4, v67, v4
	global_store_short_d16_hi v[2:3], v5, off offset:128
	v_bfe_u32 v5, v4, 16, 1
	v_add3_u32 v4, v4, v5, s30
	global_store_short_d16_hi v[2:3], v4, off offset:192
	v_mul_f32_e32 v4, v56, v56
	v_fmac_f32_e32 v4, v68, v68
	v_fmac_f32_e32 v4, v40, v40
	v_fmac_f32_e32 v4, v27, v27
	s_nop 1
	s_waitcnt lgkmcnt(0)
	v_add_f32_dpp v4, v4, v4 quad_perm:[1,0,3,2] row_mask:0xf bank_mask:0xf
	s_nop 1
	s_waitcnt lgkmcnt(0)
	v_add_f32_dpp v4, v4, v4 quad_perm:[2,3,0,1] row_mask:0xf bank_mask:0xf
	s_nop 1
	s_waitcnt lgkmcnt(0)
	v_add_f32_dpp v4, v4, v4 row_half_mirror row_mask:0xf bank_mask:0xf
	s_nop 1
	s_waitcnt lgkmcnt(0)
	v_add_f32_dpp v4, v4, v4 row_mirror row_mask:0xf bank_mask:0xf
	v_mov_b32_e32 v5, v4
	s_waitcnt lgkmcnt(0)
; __device__ __forceinline__ unsigned f2bf(float f) { unsigned u = __builtin_bit_cast(unsigned, f); return (u + 0x7fffu + ((u >> 16) & 1u)) >> 16; }
; __device__ __forceinline__ int crow(int r, int hi) { return (r & 3) + 8 * (r >> 2) + 4 * hi; }
; __device__ __forceinline__ void attn_unit(const bf16* __restrict__ P, bf16* __restrict__ MIXIN, const float* __restrict__ gn, int seq0, int h, int q0, int nt, float kmax0, float kmax1, float slope, float lam, char* lds) {
;     ...
;     for (int r = 0; r < 16; ++r) {
;       float ss = o[0][r] * o[0][r] + o[1][r] * o[1][r] + o[2][r] * o[2][r] + o[3][r] * o[3][r];
;       ss += __shfl_xor(ss, 1); ss += __shfl_xor(ss, 2); ss += __shfl_xor(ss, 4); ss += __shfl_xor(ss, 8); ss += __shfl_xor(ss, 16);
;       const float sc_ = 1.0f / sqrtf(ss * (1.0f / 128.0f) + EPS);
;       const int orow = crow(r, hie);
; #pragma unroll
;       for (int d0 = 0; d0 < 4; ++d0) Ow[(size_t)orow * DM + d0 * 32] = (bf16)f2bf(o[d0][r] * sc_ * g4[d0]);
;     }
	s_nop 0
	v_permlane16_swap_b32_e32 v4, v5
	v_add_f32_e32 v4, v4, v5
	v_fmamk_f32 v4, v4, 0x3c000000, v221
	v_cmp_gt_f32_e32 vcc, s26, v4
	v_mul_f32_e32 v5, 0x4f800000, v4
	s_nop 0
	v_cndmask_b32_e32 v4, v4, v5, vcc
	v_sqrt_f32_e32 v5, v4
	s_nop 0
	v_add_u32_e32 v11, -1, v5
	v_fma_f32 v12, -v11, v5, v4
	v_cmp_ge_f32_e64 s[0:1], 0, v12
	v_add_u32_e32 v12, 1, v5
	s_nop 0
	v_cndmask_b32_e64 v11, v5, v11, s[0:1]
	v_fma_f32 v5, -v12, v5, v4
	v_cmp_lt_f32_e64 s[0:1], 0, v5
	s_nop 1
	v_cndmask_b32_e64 v5, v11, v12, s[0:1]
	v_mul_f32_e32 v11, 0x37800000, v5
	v_cndmask_b32_e32 v5, v5, v11, vcc
	v_cmp_class_f32_e32 vcc, v4, v220
	s_nop 1
	v_cndmask_b32_e32 v4, v5, v4, vcc
	v_div_scale_f32 v5, s[0:1], v4, v4, 1.0
	v_rcp_f32_e32 v11, v5
	s_nop 0
	v_fma_f32 v12, -v5, v11, 1.0
	v_fmac_f32_e32 v11, v12, v11
	v_div_scale_f32 v12, vcc, 1.0, v4, 1.0
	v_mul_f32_e32 v13, v12, v11
	v_fma_f32 v14, -v5, v13, v12
	v_fmac_f32_e32 v13, v14, v11
	v_fma_f32 v5, -v5, v13, v12
	v_div_fmas_f32 v5, v5, v11, v13
	v_div_fixup_f32 v4, v5, v4, 1.0
	v_mul_f32_e32 v5, v68, v4
	v_mul_f32_e32 v5, v64, v5
	v_bfe_u32 v11, v5, 16, 1
	v_add3_u32 v5, v5, v11, s30
	global_store_short_d16_hi v[2:3], v5, off offset:2048
	v_mul_f32_e32 v5, v56, v4
	v_mul_f32_e32 v5, v65, v5
	v_bfe_u32 v11, v5, 16, 1
	v_add3_u32 v5, v5, v11, s30
	global_store_short_d16_hi v[2:3], v5, off offset:2112
	v_mul_f32_e32 v5, v40, v4
	v_mul_f32_e32 v5, v66, v5
	v_bfe_u32 v11, v5, 16, 1
	v_mul_f32_e32 v4, v27, v4
	v_add3_u32 v5, v5, v11, s30
	v_mul_f32_e32 v4, v67, v4
	global_store_short_d16_hi v[2:3], v5, off offset:2176
	v_bfe_u32 v5, v4, 16, 1
	v_add3_u32 v4, v4, v5, s30
	global_store_short_d16_hi v[2:3], v4, off offset:2240
	v_mul_f32_e32 v2, v39, v39
	v_fmac_f32_e32 v2, v55, v55
	v_fmac_f32_e32 v2, v24, v24
	v_fmac_f32_e32 v2, v26, v26
	s_nop 1
	s_waitcnt lgkmcnt(0)
	v_add_f32_dpp v2, v2, v2 quad_perm:[1,0,3,2] row_mask:0xf bank_mask:0xf
	s_nop 1
	s_waitcnt lgkmcnt(0)
	v_add_f32_dpp v2, v2, v2 quad_perm:[2,3,0,1] row_mask:0xf bank_mask:0xf
	s_nop 1
	s_waitcnt lgkmcnt(0)
	v_add_f32_dpp v2, v2, v2 row_half_mirror row_mask:0xf bank_mask:0xf
	s_nop 1
	s_waitcnt lgkmcnt(0)
	v_add_f32_dpp v2, v2, v2 row_mirror row_mask:0xf bank_mask:0xf
	v_mov_b32_e32 v3, v2
	s_waitcnt lgkmcnt(0)
	s_nop 0
	v_permlane16_swap_b32_e32 v2, v3
	v_add_f32_e32 v2, v2, v3
	v_fmamk_f32 v2, v2, 0x3c000000, v221
	v_cmp_gt_f32_e32 vcc, s26, v2
	v_mul_f32_e32 v3, 0x4f800000, v2
	s_nop 0
	v_cndmask_b32_e32 v2, v2, v3, vcc
	v_sqrt_f32_e32 v3, v2
	s_nop 0
	v_add_u32_e32 v4, -1, v3
	v_fma_f32 v5, -v4, v3, v2
	v_cmp_ge_f32_e64 s[0:1], 0, v5
	v_add_u32_e32 v5, 1, v3
	s_nop 0
	v_cndmask_b32_e64 v4, v3, v4, s[0:1]
	v_fma_f32 v3, -v5, v3, v2
	v_cmp_lt_f32_e64 s[0:1], 0, v3
	s_nop 1
	v_cndmask_b32_e64 v3, v4, v5, s[0:1]
	v_mul_f32_e32 v4, 0x37800000, v3
	v_cndmask_b32_e32 v3, v3, v4, vcc
	v_cmp_class_f32_e32 vcc, v2, v220
	s_nop 1
	v_cndmask_b32_e32 v2, v3, v2, vcc
	v_div_scale_f32 v3, s[0:1], v2, v2, 1.0
	v_rcp_f32_e32 v4, v3
	s_mov_b32 s0, 0x8000
	v_fma_f32 v5, -v3, v4, 1.0
	v_fmac_f32_e32 v4, v5, v4
	v_div_scale_f32 v5, vcc, 1.0, v2, 1.0
	v_mul_f32_e32 v11, v5, v4
	v_fma_f32 v12, -v3, v11, v5
	v_fmac_f32_e32 v11, v12, v4
	v_fma_f32 v3, -v3, v11, v5
	v_div_fmas_f32 v3, v3, v4, v11
	v_div_fixup_f32 v11, v3, v2, 1.0
	v_mul_f32_e32 v2, v55, v11
	v_mul_f32_e32 v2, v64, v2
	v_add_co_u32_e32 v4, vcc, s0, v0
	v_bfe_u32 v3, v2, 16, 1
	s_nop 0
	v_addc_co_u32_e32 v5, vcc, 0, v1, vcc
	s_mov_b32 s0, 0x9000
	v_add3_u32 v12, v2, v3, s30
	v_add_co_u32_e32 v2, vcc, s0, v0
	s_nop 1
	v_addc_co_u32_e32 v3, vcc, 0, v1, vcc
	global_store_short_d16_hi v[2:3], v12, off offset:-4096
	v_mul_f32_e32 v12, v39, v11
	v_mul_f32_e32 v12, v65, v12
	v_bfe_u32 v13, v12, 16, 1
	v_add3_u32 v12, v12, v13, s30
	global_store_short_d16_hi v[4:5], v12, off offset:64
	v_mul_f32_e32 v12, v24, v11
	v_mul_f32_e32 v12, v66, v12
	v_bfe_u32 v13, v12, 16, 1
	v_mul_f32_e32 v11, v26, v11
	v_add3_u32 v12, v12, v13, s30
	v_mul_f32_e32 v11, v67, v11
	global_store_short_d16_hi v[4:5], v12, off offset:128
	v_bfe_u32 v12, v11, 16, 1
	v_add3_u32 v11, v11, v12, s30
	global_store_short_d16_hi v[4:5], v11, off offset:192
	v_mul_f32_e32 v11, v38, v38
	v_fmac_f32_e32 v11, v54, v54
	v_fmac_f32_e32 v11, v23, v23
	v_fmac_f32_e32 v11, v25, v25
	s_nop 1
	s_waitcnt lgkmcnt(0)
	v_add_f32_dpp v11, v11, v11 quad_perm:[1,0,3,2] row_mask:0xf bank_mask:0xf
	s_nop 1
	s_waitcnt lgkmcnt(0)
	v_add_f32_dpp v11, v11, v11 quad_perm:[2,3,0,1] row_mask:0xf bank_mask:0xf
	s_nop 1
	s_waitcnt lgkmcnt(0)
	v_add_f32_dpp v11, v11, v11 row_half_mirror row_mask:0xf bank_mask:0xf
	s_nop 1
	s_waitcnt lgkmcnt(0)
	v_add_f32_dpp v11, v11, v11 row_mirror row_mask:0xf bank_mask:0xf
	v_mov_b32_e32 v12, v11
	s_waitcnt lgkmcnt(0)
; __device__ __forceinline__ unsigned f2bf(float f) { unsigned u = __builtin_bit_cast(unsigned, f); return (u + 0x7fffu + ((u >> 16) & 1u)) >> 16; }
; __device__ __forceinline__ int crow(int r, int hi) { return (r & 3) + 8 * (r >> 2) + 4 * hi; }
; __device__ __forceinline__ void attn_unit(const bf16* __restrict__ P, bf16* __restrict__ MIXIN, const float* __restrict__ gn, int seq0, int h, int q0, int nt, float kmax0, float kmax1, float slope, float lam, char* lds) {
;     ...
;     for (int r = 0; r < 16; ++r) {
;       float ss = o[0][r] * o[0][r] + o[1][r] * o[1][r] + o[2][r] * o[2][r] + o[3][r] * o[3][r];
;       ss += __shfl_xor(ss, 1); ss += __shfl_xor(ss, 2); ss += __shfl_xor(ss, 4); ss += __shfl_xor(ss, 8); ss += __shfl_xor(ss, 16);
;       const float sc_ = 1.0f / sqrtf(ss * (1.0f / 128.0f) + EPS);
;       const int orow = crow(r, hie);
; #pragma unroll
;       for (int d0 = 0; d0 < 4; ++d0) Ow[(size_t)orow * DM + d0 * 32] = (bf16)f2bf(o[d0][r] * sc_ * g4[d0]);
	s_nop 0
	v_permlane16_swap_b32_e32 v11, v12
	v_add_f32_e32 v11, v11, v12
	v_fmamk_f32 v11, v11, 0x3c000000, v221
	v_cmp_gt_f32_e32 vcc, s26, v11
	v_mul_f32_e32 v12, 0x4f800000, v11
	s_nop 0
	v_cndmask_b32_e32 v11, v11, v12, vcc
	v_sqrt_f32_e32 v12, v11
	s_nop 0
	v_add_u32_e32 v13, -1, v12
	v_fma_f32 v14, -v13, v12, v11
	v_cmp_ge_f32_e64 s[0:1], 0, v14
	v_add_u32_e32 v14, 1, v12
	s_nop 0
	v_cndmask_b32_e64 v13, v12, v13, s[0:1]
	v_fma_f32 v12, -v14, v12, v11
	v_cmp_lt_f32_e64 s[0:1], 0, v12
	s_nop 1
	v_cndmask_b32_e64 v12, v13, v14, s[0:1]
	v_mul_f32_e32 v13, 0x37800000, v12
	v_cndmask_b32_e32 v12, v12, v13, vcc
	v_cmp_class_f32_e32 vcc, v11, v220
	s_nop 1
	v_cndmask_b32_e32 v11, v12, v11, vcc
	v_div_scale_f32 v12, s[0:1], v11, v11, 1.0
	v_rcp_f32_e32 v13, v12
	s_nop 0
	v_fma_f32 v14, -v12, v13, 1.0
	v_fmac_f32_e32 v13, v14, v13
	v_div_scale_f32 v14, vcc, 1.0, v11, 1.0
	v_mul_f32_e32 v15, v14, v13
	v_fma_f32 v24, -v12, v15, v14
	v_fmac_f32_e32 v15, v24, v13
	v_fma_f32 v12, -v12, v15, v14
	v_div_fmas_f32 v12, v12, v13, v15
	v_div_fixup_f32 v11, v12, v11, 1.0
	v_mul_f32_e32 v12, v54, v11
	v_mul_f32_e32 v12, v64, v12
	v_bfe_u32 v13, v12, 16, 1
	v_add3_u32 v12, v12, v13, s30
	global_store_short_d16_hi v[4:5], v12, off offset:2048
	v_mul_f32_e32 v12, v38, v11
	v_mul_f32_e32 v12, v65, v12
	v_bfe_u32 v13, v12, 16, 1
	v_add3_u32 v12, v12, v13, s30
	global_store_short_d16_hi v[4:5], v12, off offset:2112
	v_mul_f32_e32 v12, v23, v11
	v_mul_f32_e32 v12, v66, v12
	v_bfe_u32 v13, v12, 16, 1
	v_mul_f32_e32 v11, v25, v11
	v_add3_u32 v12, v12, v13, s30
	v_mul_f32_e32 v11, v67, v11
	global_store_short_d16_hi v[4:5], v12, off offset:2176
	v_bfe_u32 v12, v11, 16, 1
	v_add3_u32 v11, v11, v12, s30
	global_store_short_d16_hi v[4:5], v11, off offset:2240
	v_mul_f32_e32 v4, v37, v37
	v_fmac_f32_e32 v4, v53, v53
	v_fmac_f32_e32 v4, v21, v21
	v_fmac_f32_e32 v4, v22, v22
	s_nop 1
	s_waitcnt lgkmcnt(0)
	v_add_f32_dpp v4, v4, v4 quad_perm:[1,0,3,2] row_mask:0xf bank_mask:0xf
	s_nop 1
	s_waitcnt lgkmcnt(0)
	v_add_f32_dpp v4, v4, v4 quad_perm:[2,3,0,1] row_mask:0xf bank_mask:0xf
	s_nop 1
	s_waitcnt lgkmcnt(0)
	v_add_f32_dpp v4, v4, v4 row_half_mirror row_mask:0xf bank_mask:0xf
	s_nop 1
	s_waitcnt lgkmcnt(0)
	v_add_f32_dpp v4, v4, v4 row_mirror row_mask:0xf bank_mask:0xf
	v_mov_b32_e32 v5, v4
	s_waitcnt lgkmcnt(0)
	s_nop 0
	v_permlane16_swap_b32_e32 v4, v5
	v_add_f32_e32 v4, v4, v5
	v_fmamk_f32 v4, v4, 0x3c000000, v221
	v_cmp_gt_f32_e32 vcc, s26, v4
	v_mul_f32_e32 v5, 0x4f800000, v4
	s_nop 0
	v_cndmask_b32_e32 v4, v4, v5, vcc
	v_sqrt_f32_e32 v5, v4
	s_nop 0
	v_add_u32_e32 v11, -1, v5
	v_fma_f32 v12, -v11, v5, v4
	v_cmp_ge_f32_e64 s[0:1], 0, v12
	v_add_u32_e32 v12, 1, v5
	s_nop 0
	v_cndmask_b32_e64 v11, v5, v11, s[0:1]
	v_fma_f32 v5, -v12, v5, v4
	v_cmp_lt_f32_e64 s[0:1], 0, v5
	s_nop 1
	v_cndmask_b32_e64 v5, v11, v12, s[0:1]
	v_mul_f32_e32 v11, 0x37800000, v5
	v_cndmask_b32_e32 v5, v5, v11, vcc
	v_cmp_class_f32_e32 vcc, v4, v220
	s_nop 1
	v_cndmask_b32_e32 v4, v5, v4, vcc
	v_div_scale_f32 v5, s[0:1], v4, v4, 1.0
	v_rcp_f32_e32 v11, v5
	s_nop 0
	v_fma_f32 v12, -v5, v11, 1.0
	v_fmac_f32_e32 v11, v12, v11
	v_div_scale_f32 v12, vcc, 1.0, v4, 1.0
	v_mul_f32_e32 v13, v12, v11
	v_fma_f32 v14, -v5, v13, v12
	v_fmac_f32_e32 v13, v14, v11
	v_fma_f32 v5, -v5, v13, v12
	v_div_fmas_f32 v5, v5, v11, v13
	v_div_fixup_f32 v4, v5, v4, 1.0
	v_mul_f32_e32 v5, v53, v4
	v_mul_f32_e32 v5, v64, v5
	v_bfe_u32 v11, v5, 16, 1
	v_add3_u32 v5, v5, v11, s30
	global_store_short_d16_hi v[2:3], v5, off
	v_mul_f32_e32 v5, v37, v4
	v_mul_f32_e32 v5, v65, v5
	v_bfe_u32 v11, v5, 16, 1
	v_add3_u32 v5, v5, v11, s30
	global_store_short_d16_hi v[2:3], v5, off offset:64
	v_mul_f32_e32 v5, v21, v4
	v_mul_f32_e32 v5, v66, v5
	v_bfe_u32 v11, v5, 16, 1
	v_mul_f32_e32 v4, v22, v4
	v_add3_u32 v5, v5, v11, s30
	v_mul_f32_e32 v4, v67, v4
	global_store_short_d16_hi v[2:3], v5, off offset:128
	v_bfe_u32 v5, v4, 16, 1
	v_add3_u32 v4, v4, v5, s30
	global_store_short_d16_hi v[2:3], v4, off offset:192
	v_mul_f32_e32 v4, v36, v36
	v_fmac_f32_e32 v4, v52, v52
	v_fmac_f32_e32 v4, v20, v20
	v_fmac_f32_e32 v4, v10, v10
	s_nop 1
	s_waitcnt lgkmcnt(0)
	v_add_f32_dpp v4, v4, v4 quad_perm:[1,0,3,2] row_mask:0xf bank_mask:0xf
	s_nop 1
	s_waitcnt lgkmcnt(0)
	v_add_f32_dpp v4, v4, v4 quad_perm:[2,3,0,1] row_mask:0xf bank_mask:0xf
	s_nop 1
	s_waitcnt lgkmcnt(0)
	v_add_f32_dpp v4, v4, v4 row_half_mirror row_mask:0xf bank_mask:0xf
	s_nop 1
	s_waitcnt lgkmcnt(0)
	v_add_f32_dpp v4, v4, v4 row_mirror row_mask:0xf bank_mask:0xf
	v_mov_b32_e32 v5, v4
	s_waitcnt lgkmcnt(0)
	s_nop 0
	v_permlane16_swap_b32_e32 v4, v5
	v_add_f32_e32 v4, v4, v5
	v_fmamk_f32 v4, v4, 0x3c000000, v221
	v_cmp_gt_f32_e32 vcc, s26, v4
	v_mul_f32_e32 v5, 0x4f800000, v4
	s_nop 0
	v_cndmask_b32_e32 v4, v4, v5, vcc
	v_sqrt_f32_e32 v5, v4
	s_nop 0
	v_add_u32_e32 v11, -1, v5
	v_fma_f32 v12, -v11, v5, v4
	v_cmp_ge_f32_e64 s[0:1], 0, v12
	v_add_u32_e32 v12, 1, v5
	s_nop 0
	v_cndmask_b32_e64 v11, v5, v11, s[0:1]
	v_fma_f32 v5, -v12, v5, v4
	v_cmp_lt_f32_e64 s[0:1], 0, v5
	s_nop 1
	v_cndmask_b32_e64 v5, v11, v12, s[0:1]
	v_mul_f32_e32 v11, 0x37800000, v5
	v_cndmask_b32_e32 v5, v5, v11, vcc
	v_cmp_class_f32_e32 vcc, v4, v220
	s_nop 1
	v_cndmask_b32_e32 v4, v5, v4, vcc
	v_div_scale_f32 v5, s[0:1], v4, v4, 1.0
	v_rcp_f32_e32 v11, v5
	s_nop 0
	v_fma_f32 v12, -v5, v11, 1.0
	v_fmac_f32_e32 v11, v12, v11
	v_div_scale_f32 v12, vcc, 1.0, v4, 1.0
	v_mul_f32_e32 v13, v12, v11
	v_fma_f32 v14, -v5, v13, v12
	v_fmac_f32_e32 v13, v14, v11
	v_fma_f32 v5, -v5, v13, v12
	v_div_fmas_f32 v5, v5, v11, v13
	v_div_fixup_f32 v4, v5, v4, 1.0
	v_mul_f32_e32 v5, v52, v4
	v_mul_f32_e32 v5, v64, v5
	v_bfe_u32 v11, v5, 16, 1
	v_add3_u32 v5, v5, v11, s30
	global_store_short_d16_hi v[2:3], v5, off offset:2048
	v_mul_f32_e32 v5, v36, v4
	v_mul_f32_e32 v5, v65, v5
	v_bfe_u32 v11, v5, 16, 1
	v_add3_u32 v5, v5, v11, s30
	global_store_short_d16_hi v[2:3], v5, off offset:2112
	v_mul_f32_e32 v5, v20, v4
	v_mul_f32_e32 v5, v66, v5
	v_bfe_u32 v11, v5, 16, 1
	v_mul_f32_e32 v4, v10, v4
	v_add3_u32 v5, v5, v11, s30
	v_mul_f32_e32 v4, v67, v4
	global_store_short_d16_hi v[2:3], v5, off offset:2176
	v_bfe_u32 v5, v4, 16, 1
	v_add3_u32 v4, v4, v5, s30
	global_store_short_d16_hi v[2:3], v4, off offset:2240
	v_mul_f32_e32 v2, v35, v35
	v_fmac_f32_e32 v2, v51, v51
	v_fmac_f32_e32 v2, v19, v19
	v_fmac_f32_e32 v2, v9, v9
	s_nop 1
	s_waitcnt lgkmcnt(0)
; __device__ __forceinline__ unsigned f2bf(float f) { unsigned u = __builtin_bit_cast(unsigned, f); return (u + 0x7fffu + ((u >> 16) & 1u)) >> 16; }
; __device__ __forceinline__ int crow(int r, int hi) { return (r & 3) + 8 * (r >> 2) + 4 * hi; }
; __device__ __forceinline__ void attn_unit(const bf16* __restrict__ P, bf16* __restrict__ MIXIN, const float* __restrict__ gn, int seq0, int h, int q0, int nt, float kmax0, float kmax1, float slope, float lam, char* lds) {
;     ...
;     for (int r = 0; r < 16; ++r) {
;       float ss = o[0][r] * o[0][r] + o[1][r] * o[1][r] + o[2][r] * o[2][r] + o[3][r] * o[3][r];
;       ss += __shfl_xor(ss, 1); ss += __shfl_xor(ss, 2); ss += __shfl_xor(ss, 4); ss += __shfl_xor(ss, 8); ss += __shfl_xor(ss, 16);
;       const float sc_ = 1.0f / sqrtf(ss * (1.0f / 128.0f) + EPS);
;       const int orow = crow(r, hie);
; #pragma unroll
;       for (int d0 = 0; d0 < 4; ++d0) Ow[(size_t)orow * DM + d0 * 32] = (bf16)f2bf(o[d0][r] * sc_ * g4[d0]);
	v_add_f32_dpp v2, v2, v2 quad_perm:[1,0,3,2] row_mask:0xf bank_mask:0xf
	s_nop 1
	s_waitcnt lgkmcnt(0)
	v_add_f32_dpp v2, v2, v2 quad_perm:[2,3,0,1] row_mask:0xf bank_mask:0xf
	s_nop 1
	s_waitcnt lgkmcnt(0)
	v_add_f32_dpp v2, v2, v2 row_half_mirror row_mask:0xf bank_mask:0xf
	s_nop 1
	s_waitcnt lgkmcnt(0)
	v_add_f32_dpp v2, v2, v2 row_mirror row_mask:0xf bank_mask:0xf
	v_mov_b32_e32 v3, v2
	s_waitcnt lgkmcnt(0)
	s_nop 0
	v_permlane16_swap_b32_e32 v2, v3
	v_add_f32_e32 v2, v2, v3
	v_fmamk_f32 v2, v2, 0x3c000000, v221
	v_cmp_gt_f32_e32 vcc, s26, v2
	v_mul_f32_e32 v3, 0x4f800000, v2
	s_nop 0
	v_cndmask_b32_e32 v2, v2, v3, vcc
	v_sqrt_f32_e32 v3, v2
	s_nop 0
	v_add_u32_e32 v4, -1, v3
	v_fma_f32 v5, -v4, v3, v2
	v_cmp_ge_f32_e64 s[0:1], 0, v5
	v_add_u32_e32 v5, 1, v3
	s_nop 0
	v_cndmask_b32_e64 v4, v3, v4, s[0:1]
	v_fma_f32 v3, -v5, v3, v2
	v_cmp_lt_f32_e64 s[0:1], 0, v3
	s_nop 1
	v_cndmask_b32_e64 v3, v4, v5, s[0:1]
	v_mul_f32_e32 v4, 0x37800000, v3
	v_cndmask_b32_e32 v3, v3, v4, vcc
	v_cmp_class_f32_e32 vcc, v2, v220
	s_nop 1
	v_cndmask_b32_e32 v2, v3, v2, vcc
	v_div_scale_f32 v3, s[0:1], v2, v2, 1.0
	v_rcp_f32_e32 v4, v3
	s_mov_b32 s0, 0xc000
	v_fma_f32 v5, -v3, v4, 1.0
	v_fmac_f32_e32 v4, v5, v4
	v_div_scale_f32 v5, vcc, 1.0, v2, 1.0
	v_mul_f32_e32 v10, v5, v4
	v_fma_f32 v11, -v3, v10, v5
	v_fmac_f32_e32 v10, v11, v4
	v_fma_f32 v3, -v3, v10, v5
	v_div_fmas_f32 v3, v3, v4, v10
	v_div_fixup_f32 v4, v3, v2, 1.0
	v_mul_f32_e32 v2, v51, v4
	v_mul_f32_e32 v2, v64, v2
	v_bfe_u32 v3, v2, 16, 1
	v_add3_u32 v5, v2, v3, s30
	v_add_co_u32_e32 v2, vcc, s0, v0
	s_mov_b32 s0, 0xd000
	s_nop 0
	v_addc_co_u32_e32 v3, vcc, 0, v1, vcc
	v_add_co_u32_e32 v0, vcc, s0, v0
	s_nop 1
	v_addc_co_u32_e32 v1, vcc, 0, v1, vcc
	global_store_short_d16_hi v[0:1], v5, off offset:-4096
	v_mul_f32_e32 v5, v35, v4
	v_mul_f32_e32 v5, v65, v5
	v_bfe_u32 v10, v5, 16, 1
	v_add3_u32 v5, v5, v10, s30
	global_store_short_d16_hi v[2:3], v5, off offset:64
	v_mul_f32_e32 v5, v19, v4
	v_mul_f32_e32 v5, v66, v5
	v_bfe_u32 v10, v5, 16, 1
	v_mul_f32_e32 v4, v9, v4
	v_add3_u32 v5, v5, v10, s30
	v_mul_f32_e32 v4, v67, v4
	global_store_short_d16_hi v[2:3], v5, off offset:128
	v_bfe_u32 v5, v4, 16, 1
	v_add3_u32 v4, v4, v5, s30
	global_store_short_d16_hi v[2:3], v4, off offset:192
	v_mul_f32_e32 v4, v34, v34
	v_fmac_f32_e32 v4, v50, v50
	v_fmac_f32_e32 v4, v18, v18
	v_fmac_f32_e32 v4, v8, v8
	s_nop 1
	s_waitcnt lgkmcnt(0)
	v_add_f32_dpp v4, v4, v4 quad_perm:[1,0,3,2] row_mask:0xf bank_mask:0xf
	s_nop 1
	s_waitcnt lgkmcnt(0)
	v_add_f32_dpp v4, v4, v4 quad_perm:[2,3,0,1] row_mask:0xf bank_mask:0xf
	s_nop 1
	s_waitcnt lgkmcnt(0)
	v_add_f32_dpp v4, v4, v4 row_half_mirror row_mask:0xf bank_mask:0xf
	s_nop 1
	s_waitcnt lgkmcnt(0)
	v_add_f32_dpp v4, v4, v4 row_mirror row_mask:0xf bank_mask:0xf
	v_mov_b32_e32 v5, v4
	s_waitcnt lgkmcnt(0)
	s_nop 0
	v_permlane16_swap_b32_e32 v4, v5
	v_add_f32_e32 v4, v4, v5
	v_fmamk_f32 v4, v4, 0x3c000000, v221
	v_cmp_gt_f32_e32 vcc, s26, v4
	v_mul_f32_e32 v5, 0x4f800000, v4
	s_nop 0
	v_cndmask_b32_e32 v4, v4, v5, vcc
	v_sqrt_f32_e32 v5, v4
	s_nop 0
	v_add_u32_e32 v9, -1, v5
	v_fma_f32 v10, -v9, v5, v4
	v_cmp_ge_f32_e64 s[0:1], 0, v10
	v_add_u32_e32 v10, 1, v5
	s_nop 0
	v_cndmask_b32_e64 v9, v5, v9, s[0:1]
	v_fma_f32 v5, -v10, v5, v4
	v_cmp_lt_f32_e64 s[0:1], 0, v5
	s_nop 1
	v_cndmask_b32_e64 v5, v9, v10, s[0:1]
	v_mul_f32_e32 v9, 0x37800000, v5
	v_cndmask_b32_e32 v5, v5, v9, vcc
	v_cmp_class_f32_e32 vcc, v4, v220
	s_nop 1
	v_cndmask_b32_e32 v4, v5, v4, vcc
	v_div_scale_f32 v5, s[0:1], v4, v4, 1.0
	v_rcp_f32_e32 v9, v5
	s_nop 0
	v_fma_f32 v10, -v5, v9, 1.0
	v_fmac_f32_e32 v9, v10, v9
	v_div_scale_f32 v10, vcc, 1.0, v4, 1.0
	v_mul_f32_e32 v11, v10, v9
	v_fma_f32 v12, -v5, v11, v10
	v_fmac_f32_e32 v11, v12, v9
	v_fma_f32 v5, -v5, v11, v10
	v_div_fmas_f32 v5, v5, v9, v11
	v_div_fixup_f32 v4, v5, v4, 1.0
	v_mul_f32_e32 v5, v50, v4
	v_mul_f32_e32 v5, v64, v5
	v_bfe_u32 v9, v5, 16, 1
	v_add3_u32 v5, v5, v9, s30
	global_store_short_d16_hi v[2:3], v5, off offset:2048
	v_mul_f32_e32 v5, v34, v4
	v_mul_f32_e32 v5, v65, v5
	v_bfe_u32 v9, v5, 16, 1
	v_add3_u32 v5, v5, v9, s30
	global_store_short_d16_hi v[2:3], v5, off offset:2112
	v_mul_f32_e32 v5, v18, v4
	v_mul_f32_e32 v5, v66, v5
	v_bfe_u32 v9, v5, 16, 1
	v_mul_f32_e32 v4, v8, v4
	v_add3_u32 v5, v5, v9, s30
	v_mul_f32_e32 v4, v67, v4
	global_store_short_d16_hi v[2:3], v5, off offset:2176
	v_bfe_u32 v5, v4, 16, 1
	v_add3_u32 v4, v4, v5, s30
	global_store_short_d16_hi v[2:3], v4, off offset:2240
	v_mul_f32_e32 v2, v33, v33
	v_fmac_f32_e32 v2, v49, v49
	v_fmac_f32_e32 v2, v17, v17
	v_fmac_f32_e32 v2, v7, v7
	s_nop 1
	s_waitcnt lgkmcnt(0)
; __device__ __forceinline__ unsigned f2bf(float f) { unsigned u = __builtin_bit_cast(unsigned, f); return (u + 0x7fffu + ((u >> 16) & 1u)) >> 16; }
; __device__ __forceinline__ int crow(int r, int hi) { return (r & 3) + 8 * (r >> 2) + 4 * hi; }
; __device__ __forceinline__ void attn_unit(const bf16* __restrict__ P, bf16* __restrict__ MIXIN, const float* __restrict__ gn, int seq0, int h, int q0, int nt, float kmax0, float kmax1, float slope, float lam, char* lds) {
;     ...
;     for (int r = 0; r < 16; ++r) {
;       float ss = o[0][r] * o[0][r] + o[1][r] * o[1][r] + o[2][r] * o[2][r] + o[3][r] * o[3][r];
;       ss += __shfl_xor(ss, 1); ss += __shfl_xor(ss, 2); ss += __shfl_xor(ss, 4); ss += __shfl_xor(ss, 8); ss += __shfl_xor(ss, 16);
;       const float sc_ = 1.0f / sqrtf(ss * (1.0f / 128.0f) + EPS);
;       const int orow = crow(r, hie);
; #pragma unroll
;       for (int d0 = 0; d0 < 4; ++d0) Ow[(size_t)orow * DM + d0 * 32] = (bf16)f2bf(o[d0][r] * sc_ * g4[d0]);
;     }
	v_add_f32_dpp v2, v2, v2 quad_perm:[1,0,3,2] row_mask:0xf bank_mask:0xf
	s_nop 1
	s_waitcnt lgkmcnt(0)
	v_add_f32_dpp v2, v2, v2 quad_perm:[2,3,0,1] row_mask:0xf bank_mask:0xf
	s_nop 1
	s_waitcnt lgkmcnt(0)
	v_add_f32_dpp v2, v2, v2 row_half_mirror row_mask:0xf bank_mask:0xf
	s_nop 1
	s_waitcnt lgkmcnt(0)
	v_add_f32_dpp v2, v2, v2 row_mirror row_mask:0xf bank_mask:0xf
	v_mov_b32_e32 v3, v2
	s_waitcnt lgkmcnt(0)
	s_nop 0
	v_permlane16_swap_b32_e32 v2, v3
	v_add_f32_e32 v2, v2, v3
	v_fmamk_f32 v2, v2, 0x3c000000, v221
	v_cmp_gt_f32_e32 vcc, s26, v2
	v_mul_f32_e32 v3, 0x4f800000, v2
	s_nop 0
	v_cndmask_b32_e32 v2, v2, v3, vcc
	v_sqrt_f32_e32 v3, v2
	s_nop 0
	v_add_u32_e32 v4, -1, v3
	v_fma_f32 v5, -v4, v3, v2
	v_cmp_ge_f32_e64 s[0:1], 0, v5
	v_add_u32_e32 v5, 1, v3
	s_nop 0
	v_cndmask_b32_e64 v4, v3, v4, s[0:1]
	v_fma_f32 v3, -v5, v3, v2
	v_cmp_lt_f32_e64 s[0:1], 0, v3
	s_nop 1
	v_cndmask_b32_e64 v3, v4, v5, s[0:1]
	v_mul_f32_e32 v4, 0x37800000, v3
	v_cndmask_b32_e32 v3, v3, v4, vcc
	v_cmp_class_f32_e32 vcc, v2, v220
	s_nop 1
	v_cndmask_b32_e32 v2, v3, v2, vcc
	v_div_scale_f32 v3, s[0:1], v2, v2, 1.0
	v_rcp_f32_e32 v4, v3
	s_nop 0
	v_fma_f32 v5, -v3, v4, 1.0
	v_fmac_f32_e32 v4, v5, v4
	v_div_scale_f32 v5, vcc, 1.0, v2, 1.0
	v_mul_f32_e32 v8, v5, v4
	v_fma_f32 v9, -v3, v8, v5
	v_fmac_f32_e32 v8, v9, v4
	v_fma_f32 v3, -v3, v8, v5
	v_div_fmas_f32 v3, v3, v4, v8
	v_div_fixup_f32 v2, v3, v2, 1.0
	v_mul_f32_e32 v3, v49, v2
	v_mul_f32_e32 v3, v64, v3
	v_bfe_u32 v4, v3, 16, 1
	v_add3_u32 v3, v3, v4, s30
	global_store_short_d16_hi v[0:1], v3, off
	v_mul_f32_e32 v3, v33, v2
	v_mul_f32_e32 v3, v65, v3
	v_bfe_u32 v4, v3, 16, 1
	v_add3_u32 v3, v3, v4, s30
	global_store_short_d16_hi v[0:1], v3, off offset:64
	v_mul_f32_e32 v3, v17, v2
	v_mul_f32_e32 v3, v66, v3
	v_bfe_u32 v4, v3, 16, 1
	v_mul_f32_e32 v2, v7, v2
	v_add3_u32 v3, v3, v4, s30
	v_mul_f32_e32 v2, v67, v2
	global_store_short_d16_hi v[0:1], v3, off offset:128
	v_bfe_u32 v3, v2, 16, 1
	v_add3_u32 v2, v2, v3, s30
	global_store_short_d16_hi v[0:1], v2, off offset:192
	v_mul_f32_e32 v2, v32, v32
	v_fmac_f32_e32 v2, v48, v48
	v_fmac_f32_e32 v2, v16, v16
	v_fmac_f32_e32 v2, v6, v6
	s_nop 1
	s_waitcnt lgkmcnt(0)
	v_add_f32_dpp v2, v2, v2 quad_perm:[1,0,3,2] row_mask:0xf bank_mask:0xf
	s_nop 1
	s_waitcnt lgkmcnt(0)
	v_add_f32_dpp v2, v2, v2 quad_perm:[2,3,0,1] row_mask:0xf bank_mask:0xf
	s_nop 1
	s_waitcnt lgkmcnt(0)
	v_add_f32_dpp v2, v2, v2 row_half_mirror row_mask:0xf bank_mask:0xf
	s_nop 1
	s_waitcnt lgkmcnt(0)
	v_add_f32_dpp v2, v2, v2 row_mirror row_mask:0xf bank_mask:0xf
	v_mov_b32_e32 v3, v2
	s_waitcnt lgkmcnt(0)
	s_nop 0
	v_permlane16_swap_b32_e32 v2, v3
	v_add_f32_e32 v2, v2, v3
	v_fmamk_f32 v2, v2, 0x3c000000, v221
	v_cmp_gt_f32_e32 vcc, s26, v2
	v_mul_f32_e32 v3, 0x4f800000, v2
	s_nop 0
	v_cndmask_b32_e32 v2, v2, v3, vcc
	v_sqrt_f32_e32 v3, v2
	s_nop 0
	v_add_u32_e32 v4, -1, v3
	v_fma_f32 v5, -v4, v3, v2
	v_cmp_ge_f32_e64 s[0:1], 0, v5
	v_add_u32_e32 v5, 1, v3
	s_nop 0
	v_cndmask_b32_e64 v4, v3, v4, s[0:1]
	v_fma_f32 v3, -v5, v3, v2
	v_cmp_lt_f32_e64 s[0:1], 0, v3
	s_nop 1
	v_cndmask_b32_e64 v3, v4, v5, s[0:1]
	v_mul_f32_e32 v4, 0x37800000, v3
	v_cndmask_b32_e32 v3, v3, v4, vcc
	v_cmp_class_f32_e32 vcc, v2, v220
	s_nop 1
	v_cndmask_b32_e32 v2, v3, v2, vcc
	v_div_scale_f32 v3, s[0:1], v2, v2, 1.0
	v_rcp_f32_e32 v4, v3
	s_nop 0
	v_fma_f32 v5, -v3, v4, 1.0
	v_fmac_f32_e32 v4, v5, v4
	v_div_scale_f32 v5, vcc, 1.0, v2, 1.0
	v_mul_f32_e32 v7, v5, v4
	v_fma_f32 v8, -v3, v7, v5
	v_fmac_f32_e32 v7, v8, v4
	v_fma_f32 v3, -v3, v7, v5
	v_div_fmas_f32 v3, v3, v4, v7
	v_div_fixup_f32 v2, v3, v2, 1.0
	v_mul_f32_e32 v3, v48, v2
	v_mul_f32_e32 v3, v64, v3
	v_bfe_u32 v4, v3, 16, 1
	v_add3_u32 v3, v3, v4, s30
	global_store_short_d16_hi v[0:1], v3, off offset:2048
	v_mul_f32_e32 v3, v32, v2
	v_mul_f32_e32 v3, v65, v3
	v_bfe_u32 v4, v3, 16, 1
	v_add3_u32 v3, v3, v4, s30
	global_store_short_d16_hi v[0:1], v3, off offset:2112
	v_mul_f32_e32 v3, v16, v2
	v_mul_f32_e32 v3, v66, v3
	v_bfe_u32 v4, v3, 16, 1
	v_mul_f32_e32 v2, v6, v2
	v_add3_u32 v3, v3, v4, s30
	v_mul_f32_e32 v2, v67, v2
	global_store_short_d16_hi v[0:1], v3, off offset:2176
	v_bfe_u32 v3, v2, 16, 1
	v_add3_u32 v2, v2, v3, s30
	global_store_short_d16_hi v[0:1], v2, off offset:2240
	s_branch .LBB0_291
